# baseline (speedup 1.0000x reference)
; template <int MODE>
; __device__ __forceinline__ void attn_item(const Params& P, int b, int h, int qb, char* lds) {
;     ...
;         const float nref = -m_reg;
; #pragma unroll
;         for (int r = 0; r < 16; ++r) { p0[r] = nref; p1[r] = nref; }
;       }
;       {
;         const char* kbp = K_lds + buf * 16384;
; #pragma unroll
;         for (int d0 = 0; d0 < 8; ++d0) {
;           const char* a = kbp + KSWZ(r32, (d0 * 16 + hi * 8) * 2);
;           const bf16x8 b0 = *(const bf16x8*)a;
;           const bf16x8 b1 = *(const bf16x8*)(a + 32 * 256);
;           p0 = __builtin_amdgcn_mfma_f32_32x32x16_bf16(b0, qr[d0], p0, 0, 0, 0);
;           p1 = __builtin_amdgcn_mfma_f32_32x32x16_bf16(b1, qr[d0], p1, 0, 0, 0);
;         }
;       }
;       const float NEG = -__builtin_inff();
;       if (MODE == 0) {
;       } else {
;         if (kb + 63 > q0) {
;           const int dq = qpos - kb - 4 * hi;
; #pragma unroll
;           for (int r = 0; r < 16; ++r) {
;             const int c = (r & 3) + 8 * (r >> 2);
;             if (dq - c < 0) p0[r] = NEG;
;             if (dq - c - 32 < 0) p1[r] = NEG;
;           }
;         }
;       }
;       float pmax = p0[0];
; #pragma unroll
;       for (int r = 1; r < 16; ++r) pmax = fmaxf(pmax, p0[r]);
; #pragma unroll
;       for (int r = 0; r < 16; ++r) pmax = fmaxf(pmax, p1[r]);
;       pmax = fmaxf(pmax, __shfl_xor(pmax, 32));
;       if (!(started && __all(pmax < -160.f))) {
;       float alpha = 1.f;
;       if (!started || __any(pmax > 6.f)) {
.Lmy_pr_a:
	v_add_u32_e32 v0, s9, v182
	v_add_u32_e32 v6, v0, v183
	v_add_u32_e32 v10, v0, v181
	ds_read_b128 v[212:215], v6 offset:32768
	ds_read_b128 v[6:9], v6 offset:40960
	v_add_u32_e32 v187, v0, v179
	ds_read_b128 v[216:219], v10 offset:32768
	ds_read_b128 v[10:13], v10 offset:40960
	v_add_u32_e32 v2, v0, v178
	ds_read_b128 v[220:223], v187 offset:32768
	ds_read_b128 v[188:191], v187 offset:40960
	v_add_u32_e32 v196, v0, v177
	ds_read_b128 v[224:227], v2 offset:32768
	ds_read_b128 v[192:195], v2 offset:40960
	v_add_u32_e32 v3, v0, v176
	ds_read_b128 v[228:231], v196 offset:32768
	ds_read_b128 v[196:199], v196 offset:40960
	v_add_u32_e32 v204, v0, v175
	ds_read_b128 v[232:235], v3 offset:32768
	ds_read_b128 v[200:203], v3 offset:40960
	ds_read_b128 v[236:239], v204 offset:32768
	ds_read_b128 v[204:207], v204 offset:40960
	v_add_u32_e32 v0, v0, v174
	v_xor_b32_e32 v96, 0x80000000, v186
	v_mov_b32_e32 v97, v96
	v_mov_b32_e32 v98, v96
	v_mov_b32_e32 v99, v96
	v_mov_b32_e32 v100, v96
	v_mov_b32_e32 v101, v96
	v_mov_b32_e32 v102, v96
	v_mov_b32_e32 v103, v96
	v_mov_b32_e32 v104, v96
	v_mov_b32_e32 v105, v96
	v_mov_b32_e32 v106, v96
	v_mov_b32_e32 v107, v96
	v_mov_b32_e32 v108, v96
	v_mov_b32_e32 v109, v96
	v_mov_b32_e32 v110, v96
	v_mov_b32_e32 v111, v96
	s_cmp_lg_u32 s0, 0
	s_waitcnt lgkmcnt(13)
	v_mfma_f32_32x32x16_bf16 v[112:127], v[212:215], v[156:159], v[96:111]
	ds_read_b128 v[240:243], v0 offset:32768
	ds_read_b128 v[208:211], v0 offset:40960
	s_waitcnt lgkmcnt(14)
	v_mfma_f32_32x32x16_bf16 v[96:111], v[6:9], v[156:159], v[96:111]
	s_waitcnt lgkmcnt(13)
	v_mfma_f32_32x32x16_bf16 v[112:127], v[216:219], v[152:155], v[112:127]
	s_waitcnt lgkmcnt(12)
	v_mfma_f32_32x32x16_bf16 v[96:111], v[10:13], v[152:155], v[96:111]
	s_waitcnt lgkmcnt(11)
	v_mfma_f32_32x32x16_bf16 v[112:127], v[220:223], v[148:151], v[112:127]
	s_waitcnt lgkmcnt(10)
	v_mfma_f32_32x32x16_bf16 v[96:111], v[188:191], v[148:151], v[96:111]
	s_waitcnt lgkmcnt(9)
	v_mfma_f32_32x32x16_bf16 v[112:127], v[224:227], v[144:147], v[112:127]
	s_waitcnt lgkmcnt(8)
	v_mfma_f32_32x32x16_bf16 v[96:111], v[192:195], v[144:147], v[96:111]
	s_waitcnt lgkmcnt(7)
	v_mfma_f32_32x32x16_bf16 v[112:127], v[228:231], v[140:143], v[112:127]
	s_waitcnt lgkmcnt(6)
	v_mfma_f32_32x32x16_bf16 v[96:111], v[196:199], v[140:143], v[96:111]
	s_waitcnt lgkmcnt(5)
	v_mfma_f32_32x32x16_bf16 v[112:127], v[232:235], v[136:139], v[112:127]
	s_waitcnt lgkmcnt(4)
	v_mfma_f32_32x32x16_bf16 v[96:111], v[200:203], v[136:139], v[96:111]
	s_waitcnt lgkmcnt(3)
	v_mfma_f32_32x32x16_bf16 v[112:127], v[236:239], v[132:135], v[112:127]
	s_waitcnt lgkmcnt(2)
	v_mfma_f32_32x32x16_bf16 v[96:111], v[204:207], v[132:135], v[96:111]
	s_waitcnt lgkmcnt(1)
	v_mfma_f32_32x32x16_bf16 v[112:127], v[240:243], v[128:131], v[112:127]
	s_waitcnt lgkmcnt(0)
	v_mfma_f32_32x32x16_bf16 v[96:111], v[208:211], v[128:131], v[96:111]
	s_nop 10
	v_max_f32_e32 v0, v113, v113
	v_max_f32_e32 v2, v112, v112
	v_max_f32_e32 v0, v2, v0
	v_max3_f32 v0, v0, v114, v115
	v_max3_f32 v0, v0, v116, v117
	v_max3_f32 v0, v0, v118, v119
	v_max3_f32 v0, v0, v120, v121
	v_max3_f32 v0, v0, v122, v123
	v_max3_f32 v0, v0, v124, v125
	v_max3_f32 v0, v0, v126, v127
	v_max3_f32 v0, v0, v96, v97
	v_max3_f32 v0, v0, v98, v99
	v_max3_f32 v0, v0, v100, v101
	v_max3_f32 v0, v0, v102, v103
	v_max3_f32 v0, v0, v104, v105
	v_max3_f32 v0, v0, v106, v107
	v_max3_f32 v0, v0, v108, v109
	v_max3_f32 v0, v0, v110, v111
	v_mov_b32_e32 v2, v0
	s_nop 1
	v_permlane32_swap_b32_e32 v0, v2
	v_max_f32_e32 v0, v0, v2
	s_cbranch_scc0 .LBB0_689
	v_cmp_lt_f32_e32 vcc, s46, v0
	s_cbranch_vccz .Lmy_fast0
	s_mov_b64 s[36:37], 0
	s_mov_b64 s[34:35], 0
	s_mov_b64 s[38:39], 0
	v_max_f32_e32 v2, v0, v0
	v_max_f32_e32 v2, 0, v2
	s_mov_b64 s[38:39], -1
	s_and_b64 vcc, exec, s[36:37]
	s_cbranch_vccnz .LBB0_691

; template <int MODE>
; __device__ __forceinline__ void attn_item(const Params& P, int b, int h, int qb, char* lds) {
;     ...
;       if (!started || __any(pmax > 6.f)) {
;         float delta = started ? fmaxf(pmax, 0.f) : pmax;
;         if (!(delta > -1e30f)) delta = 0.f;
;         if (started) alpha = __builtin_amdgcn_exp2f(-delta);
;         m_reg += delta;
; #pragma unroll
;         for (int r = 0; r < 16; ++r) { p0[r] -= delta; p1[r] -= delta; }
;         started = 1;
;       }
.LBB0_688:
	s_cmp_eq_u32 s0, 0
	s_cselect_b64 s[10:11], -1, 0
	v_cmp_lt_f32_e32 vcc, s47, v2
	s_nop 1
	v_cndmask_b32_e32 v2, 0, v2, vcc
	v_exp_f32_e64 v0, -v2
	v_pk_add_f32 v[112:113], v[112:113], v[2:3] op_sel_hi:[1,0] neg_lo:[0,1] neg_hi:[0,1]
	v_pk_add_f32 v[96:97], v[96:97], v[2:3] op_sel_hi:[1,0] neg_lo:[0,1] neg_hi:[0,1]
	v_pk_add_f32 v[114:115], v[114:115], v[2:3] op_sel_hi:[1,0] neg_lo:[0,1] neg_hi:[0,1]
	v_cndmask_b32_e64 v0, v0, 1.0, s[10:11]
	v_pk_add_f32 v[98:99], v[98:99], v[2:3] op_sel_hi:[1,0] neg_lo:[0,1] neg_hi:[0,1]
	v_pk_add_f32 v[116:117], v[116:117], v[2:3] op_sel_hi:[1,0] neg_lo:[0,1] neg_hi:[0,1]
	v_pk_add_f32 v[100:101], v[100:101], v[2:3] op_sel_hi:[1,0] neg_lo:[0,1] neg_hi:[0,1]
	v_pk_add_f32 v[118:119], v[118:119], v[2:3] op_sel_hi:[1,0] neg_lo:[0,1] neg_hi:[0,1]
	v_pk_add_f32 v[102:103], v[102:103], v[2:3] op_sel_hi:[1,0] neg_lo:[0,1] neg_hi:[0,1]
	v_pk_add_f32 v[120:121], v[120:121], v[2:3] op_sel_hi:[1,0] neg_lo:[0,1] neg_hi:[0,1]
	v_pk_add_f32 v[104:105], v[104:105], v[2:3] op_sel_hi:[1,0] neg_lo:[0,1] neg_hi:[0,1]
	v_pk_add_f32 v[122:123], v[122:123], v[2:3] op_sel_hi:[1,0] neg_lo:[0,1] neg_hi:[0,1]
	v_pk_add_f32 v[106:107], v[106:107], v[2:3] op_sel_hi:[1,0] neg_lo:[0,1] neg_hi:[0,1]
	v_pk_add_f32 v[124:125], v[124:125], v[2:3] op_sel_hi:[1,0] neg_lo:[0,1] neg_hi:[0,1]
	v_pk_add_f32 v[108:109], v[108:109], v[2:3] op_sel_hi:[1,0] neg_lo:[0,1] neg_hi:[0,1]
	v_pk_add_f32 v[126:127], v[126:127], v[2:3] op_sel_hi:[1,0] neg_lo:[0,1] neg_hi:[0,1]
	v_pk_add_f32 v[110:111], v[110:111], v[2:3] op_sel_hi:[1,0] neg_lo:[0,1] neg_hi:[0,1]
	v_add_f32_e32 v186, v186, v2
	s_branch .LBB0_693

; template <int MODE>
; __device__ __forceinline__ void attn_item(const Params& P, int b, int h, int qb, char* lds) {
;     ...
;       if (!(started && __all(pmax < -160.f))) {
;       float alpha = 1.f;
;       if (!started || __any(pmax > 6.f)) {
;         float delta = started ? fmaxf(pmax, 0.f) : pmax;
;         if (!(delta > -1e30f)) delta = 0.f;
;         if (started) alpha = __builtin_amdgcn_exp2f(-delta);
;         m_reg += delta;
; #pragma unroll
;         for (int r = 0; r < 16; ++r) { p0[r] -= delta; p1[r] -= delta; }
;         started = 1;
;       }
; #pragma unroll
;       for (int r = 0; r < 16; ++r) { p0[r] = __builtin_amdgcn_exp2f(p0[r]); p1[r] = __builtin_amdgcn_exp2f(p1[r]); }
.Lmy_fast0:
	v_mov_b32_e32 v0, 1.0
	s_branch .LBB0_693
